# phase_gates: the 32 four-unit workgroups skip the LDS staging they never read
# speedup vs baseline: 1.0132x; 1.0132x over previous
.LBB0_526:
	s_or_b64 exec, exec, s[0:1]
	s_mov_b64 s[0:1], -1
	s_and_b64 vcc, exec, s[10:11]
	s_waitcnt lgkmcnt(0)
	s_barrier
	s_cbranch_vccz .LBB0_862
	s_cmp_lg_u32 s76, 0x100
	s_cbranch_scc1 .Lgates_noskip
	s_cmp_lt_u32 s75, 32
	s_cbranch_scc1 .Lgates_skip
.Lgates_noskip:
	s_add_i32 s0, 0, 0x23fa0
	s_cmp_lg_u32 s0, -1
	s_cselect_b32 s0, s0, 0
	s_cselect_b32 s1, s55, 0
	v_mov_b32_e32 v2, s0
	s_add_i32 s0, 0, 0x23fa4
	s_cmp_lg_u32 s0, -1
	v_mov_b32_e32 v10, v224
	v_mov_b32_e32 v3, s1
	s_cselect_b32 s0, s0, 0
	s_cselect_b32 s1, s55, 0
	ds_read_b32 v4, v2
	s_waitcnt vmcnt(0) lgkmcnt(0)
	v_mov_b32_e32 v2, s0
	v_mov_b32_e32 v3, s1
	ds_read_b32 v2, v2
	s_waitcnt vmcnt(0) lgkmcnt(0)
	v_and_b32_e32 v1, 15, v10
	s_movk_i32 s4, 0x1010
	v_mad_u32_u24 v18, v1, s4, 0
	v_ashrrev_i32_e32 v8, 4, v10
	s_movk_i32 s4, 0x4040
	v_mov_b32_e32 v3, v0
	s_movk_i32 s6, 0x4000
	v_add_u32_e32 v12, 0x200, v10
	v_add_u32_e32 v11, 0x400, v10
	v_add_u32_e32 v13, 0x600, v10
	s_cmp_lg_u32 s57, -1
	s_movk_i32 s7, 0x3000
	s_mov_b32 s8, 0
	s_waitcnt lgkmcnt(0)
	v_readfirstlane_b32 s0, v4
	v_readfirstlane_b32 s1, v2
	s_nop 1
	v_mov_b64_e32 v[4:5], s[0:1]
	v_mad_i64_i32 v[6:7], s[0:1], v8, s4, v[4:5]
	v_lshlrev_b32_e32 v2, 2, v1
	v_lshl_add_u64 v[6:7], v[6:7], 0, v[2:3]
	v_add_co_u32_e32 v6, vcc, s6, v6
	s_nop 1
	v_addc_co_u32_e32 v7, vcc, 0, v7, vcc
	global_load_dword v100, v[6:7], off
	v_lshl_add_u32 v7, v8, 2, v18
	v_mov_b32_e32 v99, v7
	v_ashrrev_i32_e32 v8, 4, v12
	v_mad_i64_i32 v[6:7], s[0:1], v8, s4, v[4:5]
	v_lshl_add_u64 v[6:7], v[6:7], 0, v[2:3]
	v_add_co_u32_e32 v6, vcc, s6, v6
	s_nop 1
	v_addc_co_u32_e32 v7, vcc, 0, v7, vcc
	global_load_dword v101, v[6:7], off
	v_lshl_add_u32 v7, v8, 2, v18
	v_ashrrev_i32_e32 v8, 4, v11
	v_ashrrev_i32_e32 v11, 10, v11
	v_mad_i64_i32 v[6:7], s[0:1], v8, s4, v[4:5]
	v_lshl_add_u64 v[6:7], v[6:7], 0, v[2:3]
	v_add_co_u32_e32 v6, vcc, s6, v6
	s_nop 1
	v_addc_co_u32_e32 v7, vcc, 0, v7, vcc
	global_load_dword v102, v[6:7], off
	v_lshl_add_u32 v7, v8, 2, v18
	v_ashrrev_i32_e32 v8, 4, v13
	v_mad_i64_i32 v[6:7], s[0:1], v8, s4, v[4:5]
	v_lshl_add_u64 v[6:7], v[6:7], 0, v[2:3]
	v_add_co_u32_e32 v6, vcc, s6, v6
	s_nop 1
	v_addc_co_u32_e32 v7, vcc, 0, v7, vcc
	global_load_dword v103, v[6:7], off
	v_lshl_add_u32 v7, v8, 2, v18
	v_add_u32_e32 v6, 0x800, v10
	v_ashrrev_i32_e32 v7, 4, v6
	v_mad_i64_i32 v[8:9], s[0:1], v7, s4, v[4:5]
	v_lshl_add_u64 v[8:9], v[8:9], 0, v[2:3]
	v_add_co_u32_e32 v8, vcc, s6, v8
	v_lshl_add_u32 v7, v7, 2, v18
	s_nop 0
	v_addc_co_u32_e32 v9, vcc, 0, v9, vcc
	global_load_dword v104, v[8:9], off
	v_ashrrev_i32_e32 v6, 10, v6
	v_add_u32_e32 v8, 0xa00, v10
	v_ashrrev_i32_e32 v7, 4, v8
	v_mad_i64_i32 v[14:15], s[0:1], v7, s4, v[4:5]
	v_lshl_add_u64 v[14:15], v[14:15], 0, v[2:3]
	v_add_co_u32_e32 v14, vcc, s6, v14
	v_lshl_add_u32 v7, v7, 2, v18
	s_nop 0
	v_addc_co_u32_e32 v15, vcc, 0, v15, vcc
	global_load_dword v105, v[14:15], off
	v_add_u32_e32 v7, 0xc00, v10
	v_ashrrev_i32_e32 v9, 4, v7
	v_mad_i64_i32 v[14:15], s[0:1], v9, s4, v[4:5]
	v_lshl_add_u64 v[14:15], v[14:15], 0, v[2:3]
	v_add_co_u32_e32 v14, vcc, s6, v14
	v_lshl_add_u32 v9, v9, 2, v18
	s_nop 0
	v_addc_co_u32_e32 v15, vcc, 0, v15, vcc
	global_load_dword v106, v[14:15], off
	v_add_u32_e32 v9, 0xe00, v10
	v_ashrrev_i32_e32 v16, 4, v9
	v_mad_i64_i32 v[14:15], s[0:1], v16, s4, v[4:5]
	v_lshl_add_u64 v[14:15], v[14:15], 0, v[2:3]
	v_add_co_u32_e32 v14, vcc, s6, v14
	s_nop 1
	v_addc_co_u32_e32 v15, vcc, 0, v15, vcc
	global_load_dword v107, v[14:15], off
	v_lshl_add_u32 v15, v16, 2, v18
	v_add_u32_e32 v15, 0x1000, v10
	v_ashrrev_i32_e32 v14, 4, v15
	v_mad_i64_i32 v[16:17], s[0:1], v14, s4, v[4:5]
	v_lshl_add_u64 v[16:17], v[16:17], 0, v[2:3]
	v_add_co_u32_e32 v16, vcc, s6, v16
	v_lshl_add_u32 v14, v14, 2, v18
	s_nop 0
	v_addc_co_u32_e32 v17, vcc, 0, v17, vcc
	global_load_dword v108, v[16:17], off
	v_add_u32_e32 v14, 0x1200, v10
	v_ashrrev_i32_e32 v19, 4, v14
	v_mad_i64_i32 v[16:17], s[0:1], v19, s4, v[4:5]
	v_lshl_add_u64 v[16:17], v[16:17], 0, v[2:3]
	v_add_co_u32_e32 v16, vcc, s6, v16
	s_nop 1
	v_addc_co_u32_e32 v17, vcc, 0, v17, vcc
	global_load_dword v109, v[16:17], off
	v_lshl_add_u32 v17, v19, 2, v18
	v_add_u32_e32 v16, 0x1400, v10
	v_ashrrev_i32_e32 v19, 4, v16
	v_mad_i64_i32 v[16:17], s[0:1], v19, s4, v[4:5]
	v_lshl_add_u64 v[16:17], v[16:17], 0, v[2:3]
	v_add_co_u32_e32 v16, vcc, s6, v16
	s_nop 1
	v_addc_co_u32_e32 v17, vcc, 0, v17, vcc
	global_load_dword v110, v[16:17], off
	v_lshl_add_u32 v17, v19, 2, v18
	v_add_u32_e32 v16, 0x1600, v10
	v_ashrrev_i32_e32 v19, 4, v16
	v_mad_i64_i32 v[16:17], s[0:1], v19, s4, v[4:5]
	v_lshl_add_u64 v[16:17], v[16:17], 0, v[2:3]
	v_add_co_u32_e32 v16, vcc, s6, v16
	s_nop 1
	v_addc_co_u32_e32 v17, vcc, 0, v17, vcc
	global_load_dword v111, v[16:17], off
	v_lshl_add_u32 v17, v19, 2, v18
	v_add_u32_e32 v16, 0x1800, v10
	v_ashrrev_i32_e32 v19, 4, v16
	v_mad_i64_i32 v[16:17], s[0:1], v19, s4, v[4:5]
	v_lshl_add_u64 v[16:17], v[16:17], 0, v[2:3]
	v_add_co_u32_e32 v16, vcc, s6, v16
	s_nop 1
	v_addc_co_u32_e32 v17, vcc, 0, v17, vcc
	global_load_dword v112, v[16:17], off
	v_lshl_add_u32 v17, v19, 2, v18
	v_add_u32_e32 v16, 0x1a00, v10
	v_ashrrev_i32_e32 v19, 4, v16
	v_mad_i64_i32 v[16:17], s[0:1], v19, s4, v[4:5]
	v_lshl_add_u64 v[16:17], v[16:17], 0, v[2:3]
	v_add_co_u32_e32 v16, vcc, s6, v16
	s_nop 1
	v_addc_co_u32_e32 v17, vcc, 0, v17, vcc
	global_load_dword v113, v[16:17], off
	v_lshl_add_u32 v17, v19, 2, v18
	v_add_u32_e32 v16, 0x1c00, v10
	v_ashrrev_i32_e32 v19, 4, v16
	v_mad_i64_i32 v[16:17], s[0:1], v19, s4, v[4:5]
	v_lshl_add_u64 v[16:17], v[16:17], 0, v[2:3]
	v_add_co_u32_e32 v16, vcc, s6, v16
	s_nop 1
	v_addc_co_u32_e32 v17, vcc, 0, v17, vcc
	global_load_dword v114, v[16:17], off
	v_lshl_add_u32 v17, v19, 2, v18
	v_add_u32_e32 v16, 0x1e00, v10
	v_ashrrev_i32_e32 v19, 4, v16
	v_mad_i64_i32 v[16:17], s[0:1], v19, s4, v[4:5]
	v_lshl_add_u64 v[16:17], v[16:17], 0, v[2:3]
	v_add_co_u32_e32 v16, vcc, s6, v16
	s_nop 1
	v_addc_co_u32_e32 v17, vcc, 0, v17, vcc
	global_load_dword v115, v[16:17], off
	v_lshl_add_u32 v17, v19, 2, v18
	v_add_u32_e32 v16, 0x2000, v10
	v_ashrrev_i32_e32 v19, 4, v16
	v_mad_i64_i32 v[16:17], s[0:1], v19, s4, v[4:5]
	v_lshl_add_u64 v[16:17], v[16:17], 0, v[2:3]
	v_add_co_u32_e32 v16, vcc, s6, v16
	s_nop 1
	v_addc_co_u32_e32 v17, vcc, 0, v17, vcc
	global_load_dword v116, v[16:17], off
	v_lshl_add_u32 v17, v19, 2, v18
	v_add_u32_e32 v16, 0x2200, v10
	v_ashrrev_i32_e32 v19, 4, v16
	v_mad_i64_i32 v[16:17], s[0:1], v19, s4, v[4:5]
	v_lshl_add_u64 v[16:17], v[16:17], 0, v[2:3]
	v_add_co_u32_e32 v16, vcc, s6, v16
	s_nop 1
	v_addc_co_u32_e32 v17, vcc, 0, v17, vcc
	global_load_dword v117, v[16:17], off
	v_lshl_add_u32 v17, v19, 2, v18
	v_add_u32_e32 v16, 0x2400, v10
	v_ashrrev_i32_e32 v19, 4, v16
	v_mad_i64_i32 v[16:17], s[0:1], v19, s4, v[4:5]
	v_lshl_add_u64 v[16:17], v[16:17], 0, v[2:3]
	v_add_co_u32_e32 v16, vcc, s6, v16
	s_nop 1
	v_addc_co_u32_e32 v17, vcc, 0, v17, vcc
	global_load_dword v118, v[16:17], off
	v_lshl_add_u32 v17, v19, 2, v18
	v_add_u32_e32 v16, 0x2600, v10
	v_ashrrev_i32_e32 v19, 4, v16
	v_mad_i64_i32 v[16:17], s[0:1], v19, s4, v[4:5]
	v_lshl_add_u64 v[16:17], v[16:17], 0, v[2:3]
	v_add_co_u32_e32 v16, vcc, s6, v16
	s_nop 1
	v_addc_co_u32_e32 v17, vcc, 0, v17, vcc
	global_load_dword v119, v[16:17], off
	v_lshl_add_u32 v17, v19, 2, v18
	v_add_u32_e32 v16, 0x2800, v10
	v_ashrrev_i32_e32 v19, 4, v16
	v_mad_i64_i32 v[16:17], s[0:1], v19, s4, v[4:5]
	v_lshl_add_u64 v[16:17], v[16:17], 0, v[2:3]
	v_add_co_u32_e32 v16, vcc, s6, v16
	s_nop 1
	v_addc_co_u32_e32 v17, vcc, 0, v17, vcc
	global_load_dword v120, v[16:17], off
	v_lshl_add_u32 v17, v19, 2, v18
	v_add_u32_e32 v16, 0x2a00, v10
	v_ashrrev_i32_e32 v19, 4, v16
	v_mad_i64_i32 v[16:17], s[0:1], v19, s4, v[4:5]
	v_lshl_add_u64 v[16:17], v[16:17], 0, v[2:3]
	v_add_co_u32_e32 v16, vcc, s6, v16
	s_nop 1
	v_addc_co_u32_e32 v17, vcc, 0, v17, vcc
	global_load_dword v121, v[16:17], off
	v_lshl_add_u32 v17, v19, 2, v18
	v_add_u32_e32 v16, 0x2c00, v10
	v_ashrrev_i32_e32 v19, 4, v16
	v_mad_i64_i32 v[16:17], s[0:1], v19, s4, v[4:5]
	v_lshl_add_u64 v[16:17], v[16:17], 0, v[2:3]
	v_add_co_u32_e32 v16, vcc, s6, v16
	s_nop 1
	v_addc_co_u32_e32 v17, vcc, 0, v17, vcc
	global_load_dword v122, v[16:17], off
	v_lshl_add_u32 v17, v19, 2, v18
	v_add_u32_e32 v16, 0x2e00, v10
	v_ashrrev_i32_e32 v19, 4, v16
	v_mad_i64_i32 v[16:17], s[0:1], v19, s4, v[4:5]
	v_lshl_add_u64 v[16:17], v[16:17], 0, v[2:3]
	v_add_co_u32_e32 v16, vcc, s6, v16
	s_nop 1
	v_addc_co_u32_e32 v17, vcc, 0, v17, vcc
	global_load_dword v123, v[16:17], off
	v_lshl_add_u32 v17, v19, 2, v18
	v_add_u32_e32 v16, 0x3000, v10
	v_ashrrev_i32_e32 v19, 4, v16
	v_mad_i64_i32 v[16:17], s[0:1], v19, s4, v[4:5]
	v_lshl_add_u64 v[16:17], v[16:17], 0, v[2:3]
	v_add_co_u32_e32 v16, vcc, s6, v16
	s_nop 1
	v_addc_co_u32_e32 v17, vcc, 0, v17, vcc
	global_load_dword v124, v[16:17], off
	v_lshl_add_u32 v17, v19, 2, v18
	v_add_u32_e32 v16, 0x3200, v10
	v_ashrrev_i32_e32 v19, 4, v16
	v_mad_i64_i32 v[16:17], s[0:1], v19, s4, v[4:5]
	v_lshl_add_u64 v[16:17], v[16:17], 0, v[2:3]
	v_add_co_u32_e32 v16, vcc, s6, v16
	s_nop 1
	v_addc_co_u32_e32 v17, vcc, 0, v17, vcc
	global_load_dword v125, v[16:17], off
	v_lshl_add_u32 v17, v19, 2, v18
	v_add_u32_e32 v16, 0x3400, v10
	v_ashrrev_i32_e32 v19, 4, v16
	v_mad_i64_i32 v[16:17], s[0:1], v19, s4, v[4:5]
	v_lshl_add_u64 v[16:17], v[16:17], 0, v[2:3]
	v_add_co_u32_e32 v16, vcc, s6, v16
	s_nop 1
	v_addc_co_u32_e32 v17, vcc, 0, v17, vcc
	global_load_dword v126, v[16:17], off
	v_lshl_add_u32 v17, v19, 2, v18
	v_add_u32_e32 v16, 0x3600, v10
	v_ashrrev_i32_e32 v19, 4, v16
	v_mad_i64_i32 v[16:17], s[0:1], v19, s4, v[4:5]
	v_lshl_add_u64 v[16:17], v[16:17], 0, v[2:3]
	v_add_co_u32_e32 v16, vcc, s6, v16
	s_nop 1
	v_addc_co_u32_e32 v17, vcc, 0, v17, vcc
	global_load_dword v127, v[16:17], off
	v_lshl_add_u32 v17, v19, 2, v18
	v_add_u32_e32 v16, 0x3800, v10
	v_ashrrev_i32_e32 v19, 4, v16
	v_mad_i64_i32 v[16:17], s[0:1], v19, s4, v[4:5]
	v_lshl_add_u64 v[16:17], v[16:17], 0, v[2:3]
	v_add_co_u32_e32 v16, vcc, s6, v16
	s_nop 1
	v_addc_co_u32_e32 v17, vcc, 0, v17, vcc
	global_load_dword v128, v[16:17], off
	v_lshl_add_u32 v17, v19, 2, v18
	v_add_u32_e32 v16, 0x3a00, v10
	v_ashrrev_i32_e32 v19, 4, v16
	v_mad_i64_i32 v[16:17], s[0:1], v19, s4, v[4:5]
	v_lshl_add_u64 v[16:17], v[16:17], 0, v[2:3]
	v_add_co_u32_e32 v16, vcc, s6, v16
	s_nop 1
	v_addc_co_u32_e32 v17, vcc, 0, v17, vcc
	global_load_dword v129, v[16:17], off
	v_lshl_add_u32 v17, v19, 2, v18
	v_add_u32_e32 v16, 0x3c00, v10
	v_ashrrev_i32_e32 v19, 4, v16
	v_mad_i64_i32 v[16:17], s[0:1], v19, s4, v[4:5]
	v_lshl_add_u64 v[16:17], v[16:17], 0, v[2:3]
	v_add_co_u32_e32 v16, vcc, s6, v16
	s_nop 1
	v_addc_co_u32_e32 v17, vcc, 0, v17, vcc
	global_load_dword v130, v[16:17], off
	v_lshl_add_u32 v17, v19, 2, v18
	v_add_u32_e32 v16, 0x3e00, v10
	v_ashrrev_i32_e32 v16, 4, v16
	v_mad_i64_i32 v[4:5], s[0:1], v16, s4, v[4:5]
	v_lshl_add_u64 v[4:5], v[4:5], 0, v[2:3]
	v_add_co_u32_e32 v4, vcc, s6, v4
	s_cselect_b32 s0, s57, 0
	s_nop 0
	v_addc_co_u32_e32 v5, vcc, 0, v5, vcc
	global_load_dword v131, v[4:5], off
	v_lshl_add_u32 v4, v16, 2, v18
	s_cselect_b32 s1, s55, 0
	s_cmp_lg_u32 s58, -1
	v_mov_b32_e32 v5, s1
	s_cselect_b32 s1, s55, 0
	s_waitcnt vmcnt(31)
	ds_write_b32 v99, v100
	s_waitcnt vmcnt(30)
	ds_write_b32 v99, v101 offset:128
	s_waitcnt vmcnt(29)
	ds_write_b32 v99, v102 offset:256
	s_waitcnt vmcnt(28)
	ds_write_b32 v99, v103 offset:384
	s_waitcnt vmcnt(27)
	ds_write_b32 v99, v104 offset:512
	s_waitcnt vmcnt(26)
	ds_write_b32 v99, v105 offset:640
	s_waitcnt vmcnt(25)
	ds_write_b32 v99, v106 offset:768
	s_waitcnt vmcnt(24)
	ds_write_b32 v99, v107 offset:896
	s_waitcnt vmcnt(23)
	ds_write_b32 v99, v108 offset:1024
	s_waitcnt vmcnt(22)
	ds_write_b32 v99, v109 offset:1152
	s_waitcnt vmcnt(21)
	ds_write_b32 v99, v110 offset:1280
	s_waitcnt vmcnt(20)
	ds_write_b32 v99, v111 offset:1408
	s_waitcnt vmcnt(19)
	ds_write_b32 v99, v112 offset:1536
	s_waitcnt vmcnt(18)
	ds_write_b32 v99, v113 offset:1664
	s_waitcnt vmcnt(17)
	ds_write_b32 v99, v114 offset:1792
	s_waitcnt vmcnt(16)
	ds_write_b32 v99, v115 offset:1920
	s_waitcnt vmcnt(15)
	ds_write_b32 v99, v116 offset:2048
	s_waitcnt vmcnt(14)
	ds_write_b32 v99, v117 offset:2176
	s_waitcnt vmcnt(13)
	ds_write_b32 v99, v118 offset:2304
	s_waitcnt vmcnt(12)
	ds_write_b32 v99, v119 offset:2432
	s_waitcnt vmcnt(11)
	ds_write_b32 v99, v120 offset:2560
	s_waitcnt vmcnt(10)
	ds_write_b32 v99, v121 offset:2688
	s_waitcnt vmcnt(9)
	ds_write_b32 v99, v122 offset:2816
	s_waitcnt vmcnt(8)
	ds_write_b32 v99, v123 offset:2944
	s_waitcnt vmcnt(7)
	ds_write_b32 v99, v124 offset:3072
	s_waitcnt vmcnt(6)
	ds_write_b32 v99, v125 offset:3200
	s_waitcnt vmcnt(5)
	ds_write_b32 v99, v126 offset:3328
	s_waitcnt vmcnt(4)
	ds_write_b32 v99, v127 offset:3456
	s_waitcnt vmcnt(3)
	ds_write_b32 v99, v128 offset:3584
	s_waitcnt vmcnt(2)
	ds_write_b32 v99, v129 offset:3712
	s_waitcnt vmcnt(1)
	ds_write_b32 v99, v130 offset:3840
	s_waitcnt vmcnt(0)
	ds_write_b32 v99, v131 offset:3968
	v_mov_b32_e32 v4, s0
	s_cselect_b32 s0, s58, 0
	ds_read_b32 v3, v4
	s_waitcnt vmcnt(0) lgkmcnt(0)
	v_mov_b32_e32 v4, s0
	v_mov_b32_e32 v5, s1
	ds_read_b32 v4, v4
	s_waitcnt vmcnt(0) lgkmcnt(0)
	v_readfirstlane_b32 s0, v3
	s_add_u32 s0, s0, 0x2d000
	v_readfirstlane_b32 s1, v4
	s_addc_u32 s1, s1, 0
	s_cmp_lg_u32 s50, -1
	s_cselect_b32 s4, s50, 0
	s_cselect_b32 s5, s55, 0
	s_cmp_lg_u32 s51, -1
	v_mov_b32_e32 v4, s4
	v_mov_b32_e32 v5, s5
	s_cselect_b32 s4, s51, 0
	s_cselect_b32 s5, s55, 0
	ds_read_b32 v3, v4
	s_waitcnt vmcnt(0) lgkmcnt(0)
	v_mov_b32_e32 v4, s4
	v_mov_b32_e32 v5, s5
	ds_read_b32 v4, v4
	s_waitcnt vmcnt(0) lgkmcnt(0)
	v_mov_b32_e32 v5, v0
	s_waitcnt lgkmcnt(0)
	v_readfirstlane_b32 s4, v3
	v_ashrrev_i32_e32 v3, 10, v10
	v_mul_hi_i32_i24_e32 v17, 0x9000, v3
	v_readfirstlane_b32 s5, v4
	v_and_b32_e32 v4, 0x3ff, v10
	v_mul_i32_i24_e32 v16, 0x9000, v3
	v_lshlrev_b32_e32 v4, 2, v4
	v_lshl_add_u64 v[16:17], s[0:1], 0, v[16:17]
	v_lshl_add_u64 v[16:17], v[16:17], 0, v[4:5]
	v_add_co_u32_e32 v20, vcc, s6, v16
	s_add_u32 s4, s4, 0x1000
	s_nop 0
	v_addc_co_u32_e32 v21, vcc, 0, v17, vcc
	v_add_co_u32_e32 v16, vcc, s7, v16
	global_load_dword v3, v[20:21], off
	s_nop 0
	v_addc_co_u32_e32 v17, vcc, 0, v17, vcc
	global_load_dword v24, v[16:17], off
	v_ashrrev_i32_e32 v20, 10, v12
	v_and_b32_e32 v12, 0x3ff, v12
	v_mul_hi_i32_i24_e32 v21, 0x9000, v20
	v_mul_i32_i24_e32 v20, 0x9000, v20
	s_addc_u32 s5, s5, 0
	v_lshlrev_b32_e32 v16, 2, v12
	v_mov_b32_e32 v17, v0
	v_lshl_add_u64 v[20:21], s[0:1], 0, v[20:21]
	global_load_dword v19, v4, s[4:5]
	global_load_dword v12, v16, s[4:5]
	v_lshl_add_u64 v[16:17], v[20:21], 0, v[16:17]
	v_add_co_u32_e32 v20, vcc, s6, v16
	s_waitcnt vmcnt(3)
	v_add_f32_e32 v3, 1.0, v3
	v_addc_co_u32_e32 v21, vcc, 0, v17, vcc
	global_load_dword v20, v[20:21], off
	v_add_co_u32_e32 v16, vcc, s7, v16
	s_waitcnt vmcnt(2)
	v_mul_f32_e32 v22, v19, v3
	v_lshl_add_u32 v3, v10, 2, 0
	v_add_u32_e32 v23, 0x10200, v3
	v_addc_co_u32_e32 v17, vcc, 0, v17, vcc
	v_add_u32_e32 v3, 0x15200, v3
	s_waitcnt vmcnt(0)
	v_add_f32_e32 v20, 1.0, v20
	v_mul_f32_e32 v12, v12, v20
	ds_write2st64_b32 v23, v22, v12 offset1:8
	global_load_dword v12, v[16:17], off
	v_mul_hi_i32_i24_e32 v17, 0x9000, v11
	v_mul_i32_i24_e32 v16, 0x9000, v11
	v_lshl_add_u64 v[16:17], s[0:1], 0, v[16:17]
	v_lshl_add_u64 v[16:17], v[16:17], 0, v[4:5]
	v_add_co_u32_e32 v20, vcc, s6, v16
	s_waitcnt vmcnt(0)
	ds_write2st64_b32 v3, v24, v12 offset1:8
	v_addc_co_u32_e32 v21, vcc, 0, v17, vcc
	v_add_co_u32_e32 v16, vcc, s7, v16
	global_load_dword v11, v[20:21], off
	s_nop 0
	v_addc_co_u32_e32 v17, vcc, 0, v17, vcc
	global_load_dword v20, v[16:17], off
	v_ashrrev_i32_e32 v16, 10, v13
	v_and_b32_e32 v12, 0x3ff, v13
	v_mul_hi_i32_i24_e32 v17, 0x9000, v16
	v_mul_i32_i24_e32 v16, 0x9000, v16
	v_lshlrev_b32_e32 v12, 2, v12
	v_mov_b32_e32 v13, v0
	v_lshl_add_u64 v[16:17], s[0:1], 0, v[16:17]
	global_load_dword v21, v12, s[4:5]
	v_lshl_add_u64 v[12:13], v[16:17], 0, v[12:13]
	v_add_co_u32_e32 v16, vcc, s6, v12
	s_waitcnt vmcnt(2)
	v_add_f32_e32 v11, 1.0, v11
	v_addc_co_u32_e32 v17, vcc, 0, v13, vcc
	global_load_dword v16, v[16:17], off
	v_add_co_u32_e32 v12, vcc, s7, v12
	v_mul_f32_e32 v11, v19, v11
	s_nop 0
	v_addc_co_u32_e32 v13, vcc, 0, v13, vcc
	s_waitcnt vmcnt(0)
	v_add_f32_e32 v16, 1.0, v16
	v_mul_f32_e32 v16, v21, v16
	ds_write2st64_b32 v23, v11, v16 offset0:16 offset1:24
	global_load_dword v11, v[12:13], off
	v_mul_hi_i32_i24_e32 v13, 0x9000, v6
	v_mul_i32_i24_e32 v12, 0x9000, v6
	v_lshl_add_u64 v[12:13], s[0:1], 0, v[12:13]
	v_lshl_add_u64 v[12:13], v[12:13], 0, v[4:5]
	v_add_co_u32_e32 v16, vcc, s6, v12
	s_waitcnt vmcnt(0)
	ds_write2st64_b32 v3, v20, v11 offset0:16 offset1:24
	v_addc_co_u32_e32 v17, vcc, 0, v13, vcc
	v_add_co_u32_e32 v12, vcc, s7, v12
	global_load_dword v6, v[16:17], off
	s_nop 0
	v_addc_co_u32_e32 v13, vcc, 0, v13, vcc
	global_load_dword v11, v[12:13], off
	v_ashrrev_i32_e32 v16, 10, v8
	v_and_b32_e32 v8, 0x3ff, v8
	v_mul_hi_i32_i24_e32 v17, 0x9000, v16
	v_mul_i32_i24_e32 v16, 0x9000, v16
	v_lshlrev_b32_e32 v12, 2, v8
	v_mov_b32_e32 v13, v0
	v_lshl_add_u64 v[16:17], s[0:1], 0, v[16:17]
	global_load_dword v8, v12, s[4:5]
	v_lshl_add_u64 v[12:13], v[16:17], 0, v[12:13]
	v_add_co_u32_e32 v16, vcc, s6, v12
	s_waitcnt vmcnt(2)
	v_add_f32_e32 v6, 1.0, v6
	v_addc_co_u32_e32 v17, vcc, 0, v13, vcc
	global_load_dword v16, v[16:17], off
	v_add_co_u32_e32 v12, vcc, s7, v12
	v_mul_f32_e32 v6, v19, v6
	s_nop 0
	v_addc_co_u32_e32 v13, vcc, 0, v13, vcc
	s_waitcnt vmcnt(0)
	v_add_f32_e32 v16, 1.0, v16
	v_mul_f32_e32 v8, v8, v16
	ds_write2st64_b32 v23, v6, v8 offset0:32 offset1:40
	global_load_dword v6, v[12:13], off
	s_waitcnt vmcnt(0)
	ds_write2st64_b32 v3, v11, v6 offset0:32 offset1:40
	v_ashrrev_i32_e32 v6, 10, v7
	v_mul_hi_i32_i24_e32 v7, 0x9000, v6
	v_mul_i32_i24_e32 v6, 0x9000, v6
	v_lshl_add_u64 v[6:7], s[0:1], 0, v[6:7]
	v_lshl_add_u64 v[6:7], v[6:7], 0, v[4:5]
	v_add_co_u32_e32 v12, vcc, s6, v6
	s_nop 1
	v_addc_co_u32_e32 v13, vcc, 0, v7, vcc
	global_load_dword v8, v[12:13], off
	v_add_co_u32_e32 v6, vcc, s7, v6
	s_waitcnt vmcnt(0)
	v_add_f32_e32 v8, 1.0, v8
	v_mul_f32_e32 v11, v19, v8
	v_addc_co_u32_e32 v7, vcc, 0, v7, vcc
	v_ashrrev_i32_e32 v8, 10, v9
	global_load_dword v12, v[6:7], off
	v_and_b32_e32 v6, 0x3ff, v9
	v_mul_hi_i32_i24_e32 v9, 0x9000, v8
	v_mul_i32_i24_e32 v8, 0x9000, v8
	v_lshlrev_b32_e32 v6, 2, v6
	v_mov_b32_e32 v7, v0
	v_lshl_add_u64 v[8:9], s[0:1], 0, v[8:9]
	global_load_dword v13, v6, s[4:5]
	v_lshl_add_u64 v[6:7], v[8:9], 0, v[6:7]
	v_add_co_u32_e32 v8, vcc, s6, v6
	s_nop 1
	v_addc_co_u32_e32 v9, vcc, 0, v7, vcc
	v_add_co_u32_e32 v6, vcc, s7, v6
	global_load_dword v8, v[8:9], off
	s_nop 0
	v_addc_co_u32_e32 v7, vcc, 0, v7, vcc
	global_load_dword v6, v[6:7], off
	s_waitcnt vmcnt(1)
	v_add_f32_e32 v8, 1.0, v8
	v_mul_f32_e32 v8, v13, v8
	ds_write2st64_b32 v23, v11, v8 offset0:48 offset1:56
	s_waitcnt vmcnt(0)
	ds_write2st64_b32 v3, v12, v6 offset0:48 offset1:56
	v_ashrrev_i32_e32 v6, 10, v15
	v_mul_hi_i32_i24_e32 v7, 0x9000, v6
	v_mul_i32_i24_e32 v6, 0x9000, v6
	v_lshl_add_u64 v[6:7], s[0:1], 0, v[6:7]
	v_lshl_add_u64 v[4:5], v[6:7], 0, v[4:5]
	v_add_co_u32_e32 v6, vcc, s6, v4
	s_nop 1
	v_addc_co_u32_e32 v7, vcc, 0, v5, vcc
	global_load_dword v6, v[6:7], off
	v_add_co_u32_e32 v4, vcc, s7, v4
	s_nop 1
	v_addc_co_u32_e32 v5, vcc, 0, v5, vcc
	global_load_dword v9, v[4:5], off
	v_and_b32_e32 v4, 0x3ff, v14
	v_lshlrev_b32_e32 v4, 2, v4
	v_mov_b32_e32 v5, v0
	global_load_dword v11, v4, s[4:5]
	s_waitcnt vmcnt(2)
	v_add_f32_e32 v6, 1.0, v6
	v_mul_f32_e32 v8, v19, v6
	v_ashrrev_i32_e32 v6, 10, v14
	v_mul_hi_i32_i24_e32 v7, 0x9000, v6
	v_mul_i32_i24_e32 v6, 0x9000, v6
	v_lshl_add_u64 v[6:7], s[0:1], 0, v[6:7]
	v_lshl_add_u64 v[4:5], v[6:7], 0, v[4:5]
	v_add_co_u32_e32 v6, vcc, s6, v4
	v_readlane_b32 s0, v253, 18
	s_nop 0
	v_addc_co_u32_e32 v7, vcc, 0, v5, vcc
	global_load_dword v6, v[6:7], off
	v_add_co_u32_e32 v4, vcc, 0x3000, v4
	v_readlane_b32 s1, v253, 19
	s_nop 0
	v_addc_co_u32_e32 v5, vcc, 0, v5, vcc
	global_load_dword v4, v[4:5], off
	s_andn2_b64 vcc, exec, s[0:1]
	s_waitcnt vmcnt(1)
	v_add_f32_e32 v6, 1.0, v6
	v_mul_f32_e32 v6, v11, v6
	ds_write2st64_b32 v23, v8, v6 offset0:64 offset1:72
	s_waitcnt vmcnt(0)
	ds_write2st64_b32 v3, v9, v4 offset0:64 offset1:72
	s_waitcnt lgkmcnt(0)
	s_barrier
	s_cbranch_vccnz .LBB0_529
	v_readlane_b32 s8, v253, 56

.Lgates_skip:
	s_cmp_lg_u32 s57, -1
	s_cselect_b32 s0, s57, 0
	s_cselect_b32 s1, s55, 0
	s_cmp_lg_u32 s58, -1
	v_mov_b32_e32 v2, s0
	v_mov_b32_e32 v3, s1
	s_cselect_b32 s0, s58, 0
	s_cselect_b32 s1, s55, 0
	s_barrier
	ds_read_b32 v1, v2
	s_waitcnt vmcnt(0) lgkmcnt(0)
	v_mov_b32_e32 v2, s0
	v_mov_b32_e32 v3, s1
	ds_read_b32 v2, v2
	s_waitcnt vmcnt(0) lgkmcnt(0)
	v_readlane_b32 s0, v253, 20
	v_mov_b32_e32 v10, v224
	v_readlane_b32 s1, v253, 21
	s_andn2_b64 vcc, exec, s[0:1]
	s_waitcnt lgkmcnt(0)
	v_readfirstlane_b32 s9, v1
	v_readfirstlane_b32 s0, v10
	v_readfirstlane_b32 s10, v2
	s_cbranch_vccnz .LBB0_557
	v_lshlrev_b32_e32 v1, 4, v10
	v_add_u32_e32 v2, 0x2000, v1
	v_ashrrev_i32_e32 v3, 31, v2
	v_lshrrev_b32_e32 v3, 22, v3
	v_add_u32_e32 v3, v2, v3
	v_ashrrev_i32_e32 v11, 10, v3
	v_mul_i32_i24_e32 v3, 0x400, v11
	v_sub_u32_e32 v2, v2, v3
	v_lshrrev_b32_e32 v3, 4, v2
	v_bitop3_b32 v2, v3, v2, 32 bitop3:0x6c
	v_ashrrev_i32_e32 v3, 31, v2
	v_lshrrev_b32_e32 v3, 26, v3
	v_add_u32_e32 v3, v2, v3
	v_lshlrev_b32_e32 v4, 3, v11
	v_ashrrev_i32_e32 v12, 6, v3
	v_and_b32_e32 v4, -16, v4
	v_add_u32_e32 v4, v12, v4
	v_and_b32_e32 v5, 3, v12
	s_mov_b32 s4, 0x1fffe0
	v_lshrrev_b32_e32 v6, 2, v4
	v_lshlrev_b32_e32 v7, 1, v4
	v_and_or_b32 v5, v4, s4, v5
	v_and_b32_e32 v6, 4, v6
	v_and_b32_e32 v7, 24, v7
	v_and_b32_e32 v3, 0xc0, v3
	v_or3_b32 v5, v5, v6, v7
	v_sub_u32_e32 v2, v2, v3
	v_mov_b32_e32 v7, 1
	v_lshlrev_b32_e32 v6, 5, v11
	v_ashrrev_i16_sdwa v2, v7, sext(v2) dst_sel:DWORD dst_unused:UNUSED_PAD src0_sel:DWORD src1_sel:BYTE_0
	v_and_b32_e32 v6, 32, v6
	v_bfe_i32 v13, v2, 0, 16
	v_add_lshl_u32 v2, v6, v13, 1
	v_lshl_add_u32 v148, v5, 11, v2
	v_lshl_add_u32 v150, v4, 11, v2
	v_bfe_i32 v2, v10, 27, 1
	v_lshrrev_b32_e32 v2, 22, v2
	v_add_u32_e32 v2, v1, v2
	v_and_b32_e32 v2, 0xfffffc00, v2
	v_sub_u32_e32 v1, v1, v2
	v_lshrrev_b32_e32 v2, 4, v1
	v_bitop3_b32 v2, v2, v1, 32 bitop3:0x6c
	v_ashrrev_i32_e32 v1, 31, v1
	v_lshrrev_b32_e32 v1, 26, v1
	v_add_u32_e32 v1, v2, v1
	v_ashrrev_i32_e32 v14, 6, v1
	v_ashrrev_i32_e32 v1, 31, v10
	v_lshrrev_b32_e32 v1, 26, v1
	v_add_u32_e32 v1, v10, v1
	v_ashrrev_i32_e32 v15, 6, v1
	v_lshlrev_b32_e32 v1, 3, v15
	s_add_u32 s24, s9, 0x5a00000
	v_and_b32_e32 v1, -16, v1
	s_addc_u32 s25, s10, 0
	v_add_u32_e32 v1, v14, v1
	s_add_u32 s26, s9, 0x4f80000
	v_and_b32_e32 v3, 3, v14
	v_lshrrev_b32_e32 v4, 2, v1
	v_lshlrev_b32_e32 v5, 1, v1
	s_addc_u32 s27, s10, 0
	s_ashr_i32 s8, s0, 6
	v_and_or_b32 v3, v1, s4, v3
	v_and_b32_e32 v4, 4, v4
	v_and_b32_e32 v5, 24, v5
	s_ashr_i32 s1, s0, 8
	s_lshl_b32 s28, s8, 10
	v_or3_b32 v3, v3, v4, v5
	v_mul_i32_i24_e32 v5, 64, v14
	v_readlane_b32 s4, v253, 41
	v_sub_u32_e32 v2, v2, v5
	v_readlane_b32 s5, v253, 42
	s_add_u32 s18, s24, s4
	v_lshlrev_b32_e32 v4, 5, v15
	v_ashrrev_i16_sdwa v2, v7, sext(v2) dst_sel:DWORD dst_unused:UNUSED_PAD src0_sel:DWORD src1_sel:BYTE_0
	s_addc_u32 s19, s25, s5
	v_readlane_b32 s4, v253, 45
	v_and_b32_e32 v4, 32, v4
	v_bfe_i32 v16, v2, 0, 16
	v_readlane_b32 s5, v253, 46
	s_add_u32 s20, s26, s4
	v_add_lshl_u32 v2, v4, v16, 1
	s_addc_u32 s21, s27, s5
	s_add_i32 s29, s28, 0
	v_lshl_add_u32 v152, v3, 11, v2
	s_add_i32 m0, s29, 0x10000
	v_lshl_add_u32 v154, v1, 11, v2
	global_load_lds_dwordx4 v152, s[20:21]
	s_add_i32 m0, s29, 0x12000
	s_add_u32 s4, s20, 0x40000
	global_load_lds_dwordx4 v148, s[20:21]
	s_addc_u32 s5, s21, 0
	s_add_i32 m0, s29, 0x14000
	s_add_i32 s30, s29, 0x2000
	global_load_lds_dwordx4 v152, s[4:5]
	s_add_i32 m0, s29, 0x16000
	v_mov_b32_e32 v153, v0
	global_load_lds_dwordx4 v148, s[4:5]
	s_mov_b32 m0, s29
	s_add_u32 s4, s18, 0x40000
	global_load_lds_dwordx4 v154, s[18:19]
	s_mov_b32 m0, s30
	s_addc_u32 s5, s19, 0
	s_add_i32 s31, s29, 0x4000
	global_load_lds_dwordx4 v150, s[18:19]
	s_mov_b32 m0, s31
	s_add_i32 s33, s29, 0x6000
	global_load_lds_dwordx4 v154, s[4:5]
	s_mov_b32 m0, s33
	v_mov_b32_e32 v149, v0
	global_load_lds_dwordx4 v150, s[4:5]
	v_mov_b32_e32 v155, v0
	v_mov_b32_e32 v151, v0
	s_cmp_eq_u32 s1, 1
	v_lshl_add_u64 v[8:9], s[20:21], 0, v[152:153]
	v_lshl_add_u64 v[6:7], s[20:21], 0, v[148:149]
	v_lshl_add_u64 v[2:3], s[18:19], 0, v[154:155]
	s_cselect_b64 s[4:5], -1, 0
	s_cmp_lg_u32 s1, 1
	v_lshl_add_u64 v[4:5], s[18:19], 0, v[150:151]
	s_cbranch_scc1 .LBB0_541
	s_barrier
